# baseline (speedup 1.0000x reference)
; __device__ __forceinline__ void na_compute(f32x16& o0, f32x16& o1, float& m, float& lsum, const bf16x8* qf, const NaFrag& f,
;                                            bool win, const float* __restrict__ rpbrow  , const int* cidx  ) {
;     ...
;   float t[16]; float tmax = -3.0e38f;
;   if (win) {
; #pragma unroll
;     for (int r = 0; r < 16; ++r) {
;       const int ci = cidx[r];
;       const float bias = rpbrow[ci < 0 ? 0 : ci];
;       t[r] = ci >= 0 ? fmaf(s[r], C, bias * LOG2E) : -1.0e30f;
;       tmax = fmaxf(tmax, t[r]);
;     }
.LBB0_851:
	s_andn2_b64 vcc, exec, s[72:73]
	v_lshl_add_u32 v188, s82, 2, v185
	s_cbranch_vccnz .LBB0_885
	v_lshl_add_u32 v114, v154, 2, v188
	ds_read_b32 v114, v114
	v_lshl_add_u32 v115, v156, 2, v188
	ds_read_b32 v115, v115
	v_lshl_add_u32 v116, v158, 2, v188
	ds_read_b32 v116, v116
	v_lshl_add_u32 v117, v160, 2, v188
	ds_read_b32 v117, v117
	v_lshl_add_u32 v118, v162, 2, v188
	ds_read_b32 v118, v118
	v_lshl_add_u32 v119, v164, 2, v188
	ds_read_b32 v119, v119
	v_lshl_add_u32 v120, v166, 2, v188
	ds_read_b32 v120, v120
	v_lshl_add_u32 v121, v168, 2, v188
	ds_read_b32 v121, v121
	v_lshl_add_u32 v122, v170, 2, v188
	ds_read_b32 v122, v122
	v_lshl_add_u32 v123, v172, 2, v188
	ds_read_b32 v123, v123
	v_lshl_add_u32 v124, v174, 2, v188
	ds_read_b32 v124, v124
	v_lshl_add_u32 v125, v176, 2, v188
	ds_read_b32 v125, v125
	v_lshl_add_u32 v126, v178, 2, v188
	ds_read_b32 v126, v126
	v_lshl_add_u32 v127, v180, 2, v188
	ds_read_b32 v127, v127
	v_lshl_add_u32 v128, v182, 2, v188
	ds_read_b32 v128, v128
	v_lshl_add_u32 v129, v183, 2, v188
	ds_read_b32 v129, v129
	v_mov_b32_e32 v254, 0xf149f2ca
	s_waitcnt lgkmcnt(15)
	v_mul_f32_e32 v114, 0x3fb8aa3b, v114
	v_fmac_f32_e32 v114, 0x3e38aa3b, v50
	v_cndmask_b32_e64 v114, v254, v114, s[4:5]
	s_waitcnt lgkmcnt(14)
	v_mul_f32_e32 v115, 0x3fb8aa3b, v115
	v_fmac_f32_e32 v115, 0x3e38aa3b, v51
	v_cndmask_b32_e64 v115, v254, v115, s[6:7]
	s_waitcnt lgkmcnt(13)
	v_mul_f32_e32 v116, 0x3fb8aa3b, v116
	v_fmac_f32_e32 v116, 0x3e38aa3b, v52
	v_cndmask_b32_e64 v116, v254, v116, s[8:9]
	s_waitcnt lgkmcnt(12)
	v_mul_f32_e32 v117, 0x3fb8aa3b, v117
	v_fmac_f32_e32 v117, 0x3e38aa3b, v53
	v_cndmask_b32_e64 v117, v254, v117, s[10:11]
	s_waitcnt lgkmcnt(11)
	v_mul_f32_e32 v118, 0x3fb8aa3b, v118
	v_fmac_f32_e32 v118, 0x3e38aa3b, v54
	v_cndmask_b32_e64 v118, v254, v118, s[12:13]
	s_waitcnt lgkmcnt(10)
	v_mul_f32_e32 v119, 0x3fb8aa3b, v119
	v_fmac_f32_e32 v119, 0x3e38aa3b, v55
	v_cndmask_b32_e64 v119, v254, v119, s[14:15]
	s_waitcnt lgkmcnt(9)
	v_mul_f32_e32 v120, 0x3fb8aa3b, v120
	v_fmac_f32_e32 v120, 0x3e38aa3b, v56
	v_cndmask_b32_e64 v120, v254, v120, s[16:17]
	s_waitcnt lgkmcnt(8)
	v_mul_f32_e32 v121, 0x3fb8aa3b, v121
	v_fmac_f32_e32 v121, 0x3e38aa3b, v57
	v_cndmask_b32_e64 v121, v254, v121, s[18:19]
	s_waitcnt lgkmcnt(7)
	v_mul_f32_e32 v122, 0x3fb8aa3b, v122
	v_fmac_f32_e32 v122, 0x3e38aa3b, v58
	v_cndmask_b32_e64 v122, v254, v122, s[20:21]
	s_waitcnt lgkmcnt(6)
	v_mul_f32_e32 v123, 0x3fb8aa3b, v123
	v_fmac_f32_e32 v123, 0x3e38aa3b, v59
	v_cndmask_b32_e64 v123, v254, v123, s[22:23]
	s_waitcnt lgkmcnt(5)
	v_mul_f32_e32 v124, 0x3fb8aa3b, v124
	v_fmac_f32_e32 v124, 0x3e38aa3b, v60
	v_cndmask_b32_e64 v124, v254, v124, s[24:25]
	s_waitcnt lgkmcnt(4)
	v_mul_f32_e32 v125, 0x3fb8aa3b, v125
	v_fmac_f32_e32 v125, 0x3e38aa3b, v61
	v_cndmask_b32_e64 v125, v254, v125, s[26:27]
	s_waitcnt lgkmcnt(3)
	v_mul_f32_e32 v126, 0x3fb8aa3b, v126
	v_fmac_f32_e32 v126, 0x3e38aa3b, v62
	v_cndmask_b32_e64 v126, v254, v126, s[28:29]
	s_waitcnt lgkmcnt(2)
	v_mul_f32_e32 v127, 0x3fb8aa3b, v127
	v_fmac_f32_e32 v127, 0x3e38aa3b, v63
	v_cndmask_b32_e64 v127, v254, v127, s[30:31]
	s_waitcnt lgkmcnt(1)
	v_mul_f32_e32 v128, 0x3fb8aa3b, v128
	v_fmac_f32_e32 v128, 0x3e38aa3b, v64
	v_cndmask_b32_e64 v128, v254, v128, s[34:35]
	s_waitcnt lgkmcnt(0)
	v_mul_f32_e32 v129, 0x3fb8aa3b, v129
	v_fmac_f32_e32 v129, 0x3e38aa3b, v65
	v_cndmask_b32_e64 v129, v254, v129, s[36:37]
	v_max3_f32 v16, v114, s3, v115
	v_max3_f32 v16, v16, v116, v117
	v_max3_f32 v16, v16, v118, v119
	v_max3_f32 v16, v16, v120, v121
	v_max3_f32 v16, v16, v122, v123
	v_max3_f32 v16, v16, v124, v125
	v_max3_f32 v16, v16, v126, v127
	v_max3_f32 v16, v16, v128, v129

; __device__ __forceinline__ void na_compute(f32x16& o0, f32x16& o1, float& m, float& lsum, const bf16x8* qf, const NaFrag& f,
;                                            bool win, const float* __restrict__ rpbrow  , const int* cidx  ) {
;     ...
;   float t[16]; float tmax = -3.0e38f;
;   if (win) {
; #pragma unroll
;     for (int r = 0; r < 16; ++r) {
;       const int ci = cidx[r];
;       const float bias = rpbrow[ci < 0 ? 0 : ci];
;       t[r] = ci >= 0 ? fmaf(s[r], C, bias * LOG2E) : -1.0e30f;
;       tmax = fmaxf(tmax, t[r]);
;     }
.LBB0_895:
	s_andn2_b64 vcc, exec, s[72:73]
	s_cbranch_vccnz .LBB0_929
	v_lshl_add_u32 v130, v155, 2, v188
	ds_read_b32 v130, v130
	v_lshl_add_u32 v131, v157, 2, v188
	ds_read_b32 v131, v131
	v_lshl_add_u32 v132, v159, 2, v188
	ds_read_b32 v132, v132
	v_lshl_add_u32 v133, v161, 2, v188
	ds_read_b32 v133, v133
	v_lshl_add_u32 v134, v163, 2, v188
	ds_read_b32 v134, v134
	v_lshl_add_u32 v135, v165, 2, v188
	ds_read_b32 v135, v135
	v_lshl_add_u32 v136, v167, 2, v188
	ds_read_b32 v136, v136
	v_lshl_add_u32 v137, v169, 2, v188
	ds_read_b32 v137, v137
	v_lshl_add_u32 v140, v171, 2, v188
	ds_read_b32 v140, v140
	v_lshl_add_u32 v141, v173, 2, v188
	ds_read_b32 v141, v141
	v_lshl_add_u32 v138, v175, 2, v188
	ds_read_b32 v138, v138
	v_lshl_add_u32 v139, v177, 2, v188
	ds_read_b32 v139, v139
	v_lshl_add_u32 v142, v179, 2, v188
	ds_read_b32 v142, v142
	v_lshl_add_u32 v143, v181, 2, v188
	ds_read_b32 v143, v143
	v_lshl_add_u32 v144, v149, 2, v188
	ds_read_b32 v144, v144
	v_lshl_add_u32 v145, v184, 2, v188
	ds_read_b32 v145, v145
	v_mov_b32_e32 v254, 0xf149f2ca
	s_waitcnt lgkmcnt(15)
	v_mul_f32_e32 v130, 0x3fb8aa3b, v130
	v_fmac_f32_e32 v130, 0x3e38aa3b, v50
	v_cndmask_b32_e64 v130, v254, v130, s[38:39]
	s_waitcnt lgkmcnt(14)
	v_mul_f32_e32 v131, 0x3fb8aa3b, v131
	v_fmac_f32_e32 v131, 0x3e38aa3b, v51
	v_cndmask_b32_e64 v131, v254, v131, s[40:41]
	s_waitcnt lgkmcnt(13)
	v_mul_f32_e32 v132, 0x3fb8aa3b, v132
	v_fmac_f32_e32 v132, 0x3e38aa3b, v52
	v_cndmask_b32_e64 v132, v254, v132, s[42:43]
	s_waitcnt lgkmcnt(12)
	v_mul_f32_e32 v133, 0x3fb8aa3b, v133
	v_fmac_f32_e32 v133, 0x3e38aa3b, v53
	v_cndmask_b32_e64 v133, v254, v133, s[44:45]
	s_waitcnt lgkmcnt(11)
	v_mul_f32_e32 v134, 0x3fb8aa3b, v134
	v_fmac_f32_e32 v134, 0x3e38aa3b, v54
	v_cndmask_b32_e64 v134, v254, v134, s[46:47]
	s_waitcnt lgkmcnt(10)
	v_mul_f32_e32 v135, 0x3fb8aa3b, v135
	v_fmac_f32_e32 v135, 0x3e38aa3b, v55
	v_cndmask_b32_e64 v135, v254, v135, s[48:49]
	s_waitcnt lgkmcnt(9)
	v_mul_f32_e32 v136, 0x3fb8aa3b, v136
	v_fmac_f32_e32 v136, 0x3e38aa3b, v56
	v_cndmask_b32_e64 v136, v254, v136, s[50:51]
	s_waitcnt lgkmcnt(8)
	v_mul_f32_e32 v137, 0x3fb8aa3b, v137
	v_fmac_f32_e32 v137, 0x3e38aa3b, v57
	v_cndmask_b32_e64 v137, v254, v137, s[52:53]
	s_waitcnt lgkmcnt(7)
	v_mul_f32_e32 v140, 0x3fb8aa3b, v140
	v_fmac_f32_e32 v140, 0x3e38aa3b, v58
	v_cndmask_b32_e64 v140, v254, v140, s[54:55]
	s_waitcnt lgkmcnt(6)
	v_mul_f32_e32 v141, 0x3fb8aa3b, v141
	v_fmac_f32_e32 v141, 0x3e38aa3b, v59
	v_cndmask_b32_e64 v141, v254, v141, s[56:57]
	s_waitcnt lgkmcnt(5)
	v_mul_f32_e32 v138, 0x3fb8aa3b, v138
	v_fmac_f32_e32 v138, 0x3e38aa3b, v60
	v_cndmask_b32_e64 v138, v254, v138, s[58:59]
	s_waitcnt lgkmcnt(4)
	v_mul_f32_e32 v139, 0x3fb8aa3b, v139
	v_fmac_f32_e32 v139, 0x3e38aa3b, v61
	v_cndmask_b32_e64 v139, v254, v139, s[60:61]
	s_waitcnt lgkmcnt(3)
	v_mul_f32_e32 v142, 0x3fb8aa3b, v142
	v_fmac_f32_e32 v142, 0x3e38aa3b, v62
	v_cndmask_b32_e64 v142, v254, v142, s[62:63]
	s_waitcnt lgkmcnt(2)
	v_mul_f32_e32 v143, 0x3fb8aa3b, v143
	v_fmac_f32_e32 v143, 0x3e38aa3b, v63
	v_cndmask_b32_e64 v143, v254, v143, s[64:65]
	s_waitcnt lgkmcnt(1)
	v_mul_f32_e32 v144, 0x3fb8aa3b, v144
	v_fmac_f32_e32 v144, 0x3e38aa3b, v64
	v_cndmask_b32_e64 v144, v254, v144, s[66:67]
	s_waitcnt lgkmcnt(0)
	v_mul_f32_e32 v145, 0x3fb8aa3b, v145
	v_fmac_f32_e32 v145, 0x3e38aa3b, v65
	v_cndmask_b32_e64 v145, v254, v145, s[68:69]
	v_max3_f32 v50, v130, s3, v131
	v_max3_f32 v50, v50, v132, v133
	v_max3_f32 v50, v50, v134, v135
	v_max3_f32 v50, v50, v136, v137
	v_max3_f32 v50, v50, v140, v141
	v_max3_f32 v50, v50, v138, v139
	v_max3_f32 v50, v50, v142, v143
	v_max3_f32 v189, v50, v144, v145

; __device__ __forceinline__ void na_compute(f32x16& o0, f32x16& o1, float& m, float& lsum, const bf16x8* qf, const NaFrag& f,
;                                            bool win, const float* __restrict__ rpbrow  , const int* cidx  ) {
;     ...
;   float t[16]; float tmax = -3.0e38f;
;   if (win) {
; #pragma unroll
;     for (int r = 0; r < 16; ++r) {
;       const int ci = cidx[r];
;       const float bias = rpbrow[ci < 0 ? 0 : ci];
;       t[r] = ci >= 0 ? fmaf(s[r], C, bias * LOG2E) : -1.0e30f;
;       tmax = fmaxf(tmax, t[r]);
;     }
.LBB0_1910:
	s_andn2_b64 vcc, exec, s[92:93]
	v_lshl_add_u32 v191, s74, 2, v188
	s_cbranch_vccnz .LBB0_1944
	v_lshl_add_u32 v114, v154, 2, v191
	ds_read_b32 v114, v114
	v_lshl_add_u32 v115, v156, 2, v191
	ds_read_b32 v115, v115
	v_lshl_add_u32 v116, v158, 2, v191
	ds_read_b32 v116, v116
	v_lshl_add_u32 v117, v160, 2, v191
	ds_read_b32 v117, v117
	v_lshl_add_u32 v118, v162, 2, v191
	ds_read_b32 v118, v118
	v_lshl_add_u32 v119, v164, 2, v191
	ds_read_b32 v119, v119
	v_lshl_add_u32 v120, v166, 2, v191
	ds_read_b32 v120, v120
	v_lshl_add_u32 v121, v168, 2, v191
	ds_read_b32 v121, v121
	v_lshl_add_u32 v122, v170, 2, v191
	ds_read_b32 v122, v122
	v_lshl_add_u32 v123, v172, 2, v191
	ds_read_b32 v123, v123
	v_lshl_add_u32 v124, v177, 2, v191
	ds_read_b32 v124, v124
	v_lshl_add_u32 v125, v179, 2, v191
	ds_read_b32 v125, v125
	v_lshl_add_u32 v126, v181, 2, v191
	ds_read_b32 v126, v126
	v_lshl_add_u32 v127, v183, 2, v191
	ds_read_b32 v127, v127
	v_lshl_add_u32 v128, v149, 2, v191
	ds_read_b32 v128, v128
	v_lshl_add_u32 v129, v186, 2, v191
	ds_read_b32 v129, v129
	v_mov_b32_e32 v254, 0xf149f2ca
	s_waitcnt lgkmcnt(15)
	v_mul_f32_e32 v114, 0x3fb8aa3b, v114
	v_fmac_f32_e32 v114, 0x3e38aa3b, v50
	v_cndmask_b32_e64 v114, v254, v114, s[6:7]
	s_waitcnt lgkmcnt(14)
	v_mul_f32_e32 v115, 0x3fb8aa3b, v115
	v_fmac_f32_e32 v115, 0x3e38aa3b, v51
	v_cndmask_b32_e64 v115, v254, v115, s[8:9]
	s_waitcnt lgkmcnt(13)
	v_mul_f32_e32 v116, 0x3fb8aa3b, v116
	v_fmac_f32_e32 v116, 0x3e38aa3b, v52
	v_cndmask_b32_e64 v116, v254, v116, s[10:11]
	s_waitcnt lgkmcnt(12)
	v_mul_f32_e32 v117, 0x3fb8aa3b, v117
	v_fmac_f32_e32 v117, 0x3e38aa3b, v53
	v_cndmask_b32_e64 v117, v254, v117, s[12:13]
	s_waitcnt lgkmcnt(11)
	v_mul_f32_e32 v118, 0x3fb8aa3b, v118
	v_fmac_f32_e32 v118, 0x3e38aa3b, v54
	v_cndmask_b32_e64 v118, v254, v118, s[14:15]
	s_waitcnt lgkmcnt(10)
	v_mul_f32_e32 v119, 0x3fb8aa3b, v119
	v_fmac_f32_e32 v119, 0x3e38aa3b, v55
	v_cndmask_b32_e64 v119, v254, v119, s[16:17]
	s_waitcnt lgkmcnt(9)
	v_mul_f32_e32 v120, 0x3fb8aa3b, v120
	v_fmac_f32_e32 v120, 0x3e38aa3b, v56
	v_cndmask_b32_e64 v120, v254, v120, s[18:19]
	s_waitcnt lgkmcnt(8)
	v_mul_f32_e32 v121, 0x3fb8aa3b, v121
	v_fmac_f32_e32 v121, 0x3e38aa3b, v57
	v_cndmask_b32_e64 v121, v254, v121, s[20:21]
	s_waitcnt lgkmcnt(7)
	v_mul_f32_e32 v122, 0x3fb8aa3b, v122
	v_fmac_f32_e32 v122, 0x3e38aa3b, v58
	v_cndmask_b32_e64 v122, v254, v122, s[22:23]
	s_waitcnt lgkmcnt(6)
	v_mul_f32_e32 v123, 0x3fb8aa3b, v123
	v_fmac_f32_e32 v123, 0x3e38aa3b, v59
	v_cndmask_b32_e64 v123, v254, v123, s[24:25]
	s_waitcnt lgkmcnt(5)
	v_mul_f32_e32 v124, 0x3fb8aa3b, v124
	v_fmac_f32_e32 v124, 0x3e38aa3b, v60
	v_cndmask_b32_e64 v124, v254, v124, s[26:27]
	s_waitcnt lgkmcnt(4)
	v_mul_f32_e32 v125, 0x3fb8aa3b, v125
	v_fmac_f32_e32 v125, 0x3e38aa3b, v61
	v_cndmask_b32_e64 v125, v254, v125, s[28:29]
	s_waitcnt lgkmcnt(3)
	v_mul_f32_e32 v126, 0x3fb8aa3b, v126
	v_fmac_f32_e32 v126, 0x3e38aa3b, v62
	v_cndmask_b32_e64 v126, v254, v126, s[30:31]
	s_waitcnt lgkmcnt(2)
	v_mul_f32_e32 v127, 0x3fb8aa3b, v127
	v_fmac_f32_e32 v127, 0x3e38aa3b, v63
	v_cndmask_b32_e64 v127, v254, v127, s[34:35]
	s_waitcnt lgkmcnt(1)
	v_mul_f32_e32 v128, 0x3fb8aa3b, v128
	v_fmac_f32_e32 v128, 0x3e38aa3b, v64
	v_cndmask_b32_e64 v128, v254, v128, s[36:37]
	s_waitcnt lgkmcnt(0)
	v_mul_f32_e32 v129, 0x3fb8aa3b, v129
	v_fmac_f32_e32 v129, 0x3e38aa3b, v65
	v_cndmask_b32_e64 v129, v254, v129, s[38:39]
	v_max3_f32 v16, v114, s2, v115
	v_max3_f32 v16, v16, v116, v117
	v_max3_f32 v16, v16, v118, v119
	v_max3_f32 v16, v16, v120, v121
	v_max3_f32 v16, v16, v122, v123
	v_max3_f32 v16, v16, v124, v125
	v_max3_f32 v16, v16, v126, v127
	v_max3_f32 v16, v16, v128, v129

; __device__ __forceinline__ void na_compute(f32x16& o0, f32x16& o1, float& m, float& lsum, const bf16x8* qf, const NaFrag& f,
;                                            bool win, const float* __restrict__ rpbrow  , const int* cidx  ) {
;     ...
;   float t[16]; float tmax = -3.0e38f;
;   if (win) {
; #pragma unroll
;     for (int r = 0; r < 16; ++r) {
;       const int ci = cidx[r];
;       const float bias = rpbrow[ci < 0 ? 0 : ci];
;       t[r] = ci >= 0 ? fmaf(s[r], C, bias * LOG2E) : -1.0e30f;
;       tmax = fmaxf(tmax, t[r]);
;     }
.LBB0_1954:
	s_andn2_b64 vcc, exec, s[92:93]
	s_cbranch_vccnz .LBB0_1988
	v_lshl_add_u32 v130, v155, 2, v191
	ds_read_b32 v130, v130
	v_lshl_add_u32 v131, v157, 2, v191
	ds_read_b32 v131, v131
	v_lshl_add_u32 v132, v159, 2, v191
	ds_read_b32 v132, v132
	v_lshl_add_u32 v133, v161, 2, v191
	ds_read_b32 v133, v133
	v_lshl_add_u32 v134, v163, 2, v191
	ds_read_b32 v134, v134
	v_lshl_add_u32 v135, v165, 2, v191
	ds_read_b32 v135, v135
	v_lshl_add_u32 v136, v167, 2, v191
	ds_read_b32 v136, v136
	v_lshl_add_u32 v137, v169, 2, v191
	ds_read_b32 v137, v137
	v_lshl_add_u32 v140, v171, 2, v191
	ds_read_b32 v140, v140
	v_lshl_add_u32 v141, v173, 2, v191
	ds_read_b32 v141, v141
	v_lshl_add_u32 v138, v178, 2, v191
	ds_read_b32 v138, v138
	v_lshl_add_u32 v139, v180, 2, v191
	ds_read_b32 v139, v139
	v_lshl_add_u32 v142, v182, 2, v191
	ds_read_b32 v142, v142
	v_lshl_add_u32 v143, v184, 2, v191
	ds_read_b32 v143, v143
	v_lshl_add_u32 v144, v185, 2, v191
	ds_read_b32 v144, v144
	v_lshl_add_u32 v145, v187, 2, v191
	ds_read_b32 v145, v145
	v_mov_b32_e32 v254, 0xf149f2ca
	s_waitcnt lgkmcnt(15)
	v_mul_f32_e32 v130, 0x3fb8aa3b, v130
	v_fmac_f32_e32 v130, 0x3e38aa3b, v50
	v_cndmask_b32_e64 v130, v254, v130, s[40:41]
	s_waitcnt lgkmcnt(14)
	v_mul_f32_e32 v131, 0x3fb8aa3b, v131
	v_fmac_f32_e32 v131, 0x3e38aa3b, v51
	v_cndmask_b32_e64 v131, v254, v131, s[42:43]
	s_waitcnt lgkmcnt(13)
	v_mul_f32_e32 v132, 0x3fb8aa3b, v132
	v_fmac_f32_e32 v132, 0x3e38aa3b, v52
	v_cndmask_b32_e64 v132, v254, v132, s[44:45]
	s_waitcnt lgkmcnt(12)
	v_mul_f32_e32 v133, 0x3fb8aa3b, v133
	v_fmac_f32_e32 v133, 0x3e38aa3b, v53
	v_cndmask_b32_e64 v133, v254, v133, s[46:47]
	s_waitcnt lgkmcnt(11)
	v_mul_f32_e32 v134, 0x3fb8aa3b, v134
	v_fmac_f32_e32 v134, 0x3e38aa3b, v54
	v_cndmask_b32_e64 v134, v254, v134, s[48:49]
	s_waitcnt lgkmcnt(10)
	v_mul_f32_e32 v135, 0x3fb8aa3b, v135
	v_fmac_f32_e32 v135, 0x3e38aa3b, v55
	v_cndmask_b32_e64 v135, v254, v135, s[50:51]
	s_waitcnt lgkmcnt(9)
	v_mul_f32_e32 v136, 0x3fb8aa3b, v136
	v_fmac_f32_e32 v136, 0x3e38aa3b, v56
	v_cndmask_b32_e64 v136, v254, v136, s[52:53]
	s_waitcnt lgkmcnt(8)
	v_mul_f32_e32 v137, 0x3fb8aa3b, v137
	v_fmac_f32_e32 v137, 0x3e38aa3b, v57
	v_cndmask_b32_e64 v137, v254, v137, s[54:55]
	s_waitcnt lgkmcnt(7)
	v_mul_f32_e32 v140, 0x3fb8aa3b, v140
	v_fmac_f32_e32 v140, 0x3e38aa3b, v58
	v_cndmask_b32_e64 v140, v254, v140, s[56:57]
	s_waitcnt lgkmcnt(6)
	v_mul_f32_e32 v141, 0x3fb8aa3b, v141
	v_fmac_f32_e32 v141, 0x3e38aa3b, v59
	v_cndmask_b32_e64 v141, v254, v141, s[58:59]
	s_waitcnt lgkmcnt(5)
	v_mul_f32_e32 v138, 0x3fb8aa3b, v138
	v_fmac_f32_e32 v138, 0x3e38aa3b, v60
	v_cndmask_b32_e64 v138, v254, v138, s[60:61]
	s_waitcnt lgkmcnt(4)
	v_mul_f32_e32 v139, 0x3fb8aa3b, v139
	v_fmac_f32_e32 v139, 0x3e38aa3b, v61
	v_cndmask_b32_e64 v139, v254, v139, s[62:63]
	s_waitcnt lgkmcnt(3)
	v_mul_f32_e32 v142, 0x3fb8aa3b, v142
	v_fmac_f32_e32 v142, 0x3e38aa3b, v62
	v_cndmask_b32_e64 v142, v254, v142, s[64:65]
	s_waitcnt lgkmcnt(2)
	v_mul_f32_e32 v143, 0x3fb8aa3b, v143
	v_fmac_f32_e32 v143, 0x3e38aa3b, v63
	v_cndmask_b32_e64 v143, v254, v143, s[66:67]
	s_waitcnt lgkmcnt(1)
	v_mul_f32_e32 v144, 0x3fb8aa3b, v144
	v_fmac_f32_e32 v144, 0x3e38aa3b, v64
	v_cndmask_b32_e64 v144, v254, v144, s[68:69]
	s_waitcnt lgkmcnt(0)
	v_mul_f32_e32 v145, 0x3fb8aa3b, v145
	v_fmac_f32_e32 v145, 0x3e38aa3b, v65
	v_cndmask_b32_e64 v145, v254, v145, s[70:71]
	v_max3_f32 v50, v130, s2, v131
	v_max3_f32 v50, v50, v132, v133
	v_max3_f32 v50, v50, v134, v135
	v_max3_f32 v50, v50, v136, v137
	v_max3_f32 v50, v50, v140, v141
	v_max3_f32 v50, v50, v138, v139
	v_max3_f32 v50, v50, v142, v143
	v_max3_f32 v194, v50, v144, v145
